# baseline (speedup 1.0000x reference)
; __device__ __forceinline__ void preproc_phase(Frame& F, int layer, int b, int cu_lo, int ncu) {
;     ...
;         {   float mq2 = 0.f, mk2 = 0.f;
; #pragma unroll
;             for (int a = 0; a < 4; ++a) { const bf16_t* rp = proj + (size_t)(t0 + a) * NP + c0; float sq = 0.f, sk = 0.f;
; #pragma unroll
;                 for (int hf = 0; hf < 2; ++hf) { const u32x4 qv = *(const u32x4*)(rp + C_FQ + 8 * hf), kv = *(const u32x4*)(rp + C_FK + 8 * hf);
;                     sq += (bflo(qv.x) * bflo(qv.x) + bfhi(qv.x) * bfhi(qv.x)) + (bflo(qv.y) * bflo(qv.y) + bfhi(qv.y) * bfhi(qv.y)) + (bflo(qv.z) * bflo(qv.z) + bfhi(qv.z) * bfhi(qv.z)) + (bflo(qv.w) * bflo(qv.w) + bfhi(qv.w) * bfhi(qv.w));
;                     sk += (bflo(kv.x) * bflo(kv.x) + bfhi(kv.x) * bfhi(kv.x)) + (bflo(kv.y) * bflo(kv.y) + bfhi(kv.y) * bfhi(kv.y)) + (bflo(kv.z) * bflo(kv.z) + bfhi(kv.z) * bfhi(kv.z)) + (bflo(kv.w) * bflo(kv.w) + bfhi(kv.w) * bfhi(kv.w)); }
;                 sq += __shfl_xor(sq, 1); sq += __shfl_xor(sq, 2); sq += __shfl_xor(sq, 4); sk += __shfl_xor(sk, 1); sk += __shfl_xor(sk, 2); sk += __shfl_xor(sk, 4);
;                 mq2 = fmaxf(mq2, sq); mk2 = fmaxf(mk2, sk); }
;             if ((F.lane & 7) == 0) { atomicMax(nrm, __builtin_bit_cast(unsigned, mq2 * 1.001f)); atomicMax(nrm + 8, __builtin_bit_cast(unsigned, mk2 * 1.001f)); } }
.LBB0_295:
	s_lshl_b32 s26, s48, 2
	v_mad_i64_i32 v[6:7], s[0:1], s26, v230, v[84:85]
	s_or_b32 s24, s26, 1
	s_or_b32 s22, s26, 2
	s_or_b32 s20, s26, 3
	v_mad_i64_i32 v[178:179], s[0:1], s24, v230, v[84:85]
	v_mad_i64_i32 v[180:181], s[0:1], s22, v230, v[84:85]
	v_mad_i64_i32 v[182:183], s[0:1], s20, v230, v[84:85]
	v_add_co_u32_e32 v184, vcc, 0x2800, v6
	s_nop 1
	v_addc_co_u32_e32 v185, vcc, 0, v7, vcc
	global_load_dwordx4 v[110:113], v[184:185], off
	global_load_dwordx4 v[114:117], v[184:185], off offset:16
	global_load_dwordx4 v[118:121], v[184:185], off offset:2048
	global_load_dwordx4 v[122:125], v[184:185], off offset:2064
	v_add_co_u32_e32 v184, vcc, 0x2800, v178
	s_nop 1
	v_addc_co_u32_e32 v185, vcc, 0, v179, vcc
	global_load_dwordx4 v[126:129], v[184:185], off
	global_load_dwordx4 v[130:133], v[184:185], off offset:16
	global_load_dwordx4 v[134:137], v[184:185], off offset:2048
	global_load_dwordx4 v[138:141], v[184:185], off offset:2064
	v_add_co_u32_e32 v184, vcc, 0x2800, v180
	s_nop 1
	v_addc_co_u32_e32 v185, vcc, 0, v181, vcc
	global_load_dwordx4 v[186:189], v[184:185], off
	global_load_dwordx4 v[190:193], v[184:185], off offset:16
	global_load_dwordx4 v[194:197], v[184:185], off offset:2048
	global_load_dwordx4 v[198:201], v[184:185], off offset:2064
	v_add_co_u32_e32 v184, vcc, 0x2800, v182
	s_nop 1
	v_addc_co_u32_e32 v185, vcc, 0, v183, vcc
	global_load_dwordx4 v[202:205], v[184:185], off
	global_load_dwordx4 v[206:209], v[184:185], off offset:16
	global_load_dwordx4 v[210:213], v[184:185], off offset:2048
	global_load_dwordx4 v[214:217], v[184:185], off offset:2064
	v_add_co_u32_e32 v10, vcc, 0x2000, v6
	s_or_b32 s24, s26, 1
	s_nop 0
	v_addc_co_u32_e32 v11, vcc, 0, v7, vcc
	v_mov_b32_e32 v2, v110
	v_mov_b32_e32 v3, v111
	v_mov_b32_e32 v4, v112
	v_mov_b32_e32 v5, v113
	v_add_co_u32_e32 v12, vcc, 0x3000, v6
	s_or_b32 s22, s26, 2
	s_nop 0
	v_addc_co_u32_e32 v13, vcc, 0, v7, vcc
	v_mov_b32_e32 v6, v118
	v_mov_b32_e32 v7, v119
	v_mov_b32_e32 v8, v120
	v_mov_b32_e32 v9, v121
	s_or_b32 s20, s26, 3
	s_waitcnt vmcnt(0) lgkmcnt(0)
	v_lshlrev_b32_e32 v14, 16, v2
	v_and_b32_e32 v2, 0xffff0000, v2
	v_mul_f32_e32 v2, v2, v2
	v_fmac_f32_e32 v2, v14, v14
	v_lshlrev_b32_e32 v14, 16, v3
	v_and_b32_e32 v3, 0xffff0000, v3
	v_mul_f32_e32 v3, v3, v3
	v_fmac_f32_e32 v3, v14, v14
	v_add_f32_e32 v2, v2, v3
	v_lshlrev_b32_e32 v3, 16, v4
	v_and_b32_e32 v4, 0xffff0000, v4
	v_mul_f32_e32 v4, v4, v4
	v_fmac_f32_e32 v4, v3, v3
	v_add_f32_e32 v2, v4, v2
	v_and_b32_e32 v4, 0xffff0000, v5
	v_lshlrev_b32_e32 v3, 16, v5
	v_mul_f32_e32 v4, v4, v4
	v_fmac_f32_e32 v4, v3, v3
	v_and_b32_e32 v3, 0xffff0000, v6
	v_add_f32_e32 v14, v4, v2
	v_lshlrev_b32_e32 v2, 16, v6
	v_mul_f32_e32 v3, v3, v3
	v_and_b32_e32 v4, 0xffff0000, v7
	v_fmac_f32_e32 v3, v2, v2
	v_lshlrev_b32_e32 v2, 16, v7
	v_mul_f32_e32 v4, v4, v4
	v_fmac_f32_e32 v4, v2, v2
	v_add_f32_e32 v2, v3, v4
	v_and_b32_e32 v4, 0xffff0000, v8
	v_lshlrev_b32_e32 v3, 16, v8
	v_mul_f32_e32 v4, v4, v4
	v_fmac_f32_e32 v4, v3, v3
	v_add_f32_e32 v2, v4, v2
	v_and_b32_e32 v4, 0xffff0000, v9
	v_lshlrev_b32_e32 v3, 16, v9
	v_mul_f32_e32 v4, v4, v4
	v_fmac_f32_e32 v4, v3, v3
	v_add_f32_e32 v15, v4, v2
	v_mov_b32_e32 v2, v114
	v_mov_b32_e32 v3, v115
	v_mov_b32_e32 v4, v116
	v_mov_b32_e32 v5, v117
	v_mov_b32_e32 v6, v122
	v_mov_b32_e32 v7, v123
	v_mov_b32_e32 v8, v124
	v_mov_b32_e32 v9, v125
	s_waitcnt lgkmcnt(0)
	v_lshlrev_b32_e32 v10, 16, v2
	v_and_b32_e32 v2, 0xffff0000, v2
	v_mul_f32_e32 v2, v2, v2
	v_fmac_f32_e32 v2, v10, v10
	v_lshlrev_b32_e32 v10, 16, v3
	v_and_b32_e32 v3, 0xffff0000, v3
	v_mul_f32_e32 v3, v3, v3
	v_fmac_f32_e32 v3, v10, v10
	v_add_f32_e32 v2, v2, v3
	v_lshlrev_b32_e32 v3, 16, v4
	v_and_b32_e32 v4, 0xffff0000, v4
	v_mul_f32_e32 v4, v4, v4
	v_fmac_f32_e32 v4, v3, v3
	v_add_f32_e32 v2, v4, v2
	v_and_b32_e32 v4, 0xffff0000, v5
	v_lshlrev_b32_e32 v3, 16, v5
	v_mul_f32_e32 v4, v4, v4
	v_fmac_f32_e32 v4, v3, v3
	v_add_f32_e32 v2, v4, v2
	v_and_b32_e32 v4, 0xffff0000, v6
	v_lshlrev_b32_e32 v3, 16, v6
	v_mul_f32_e32 v4, v4, v4
	v_and_b32_e32 v5, 0xffff0000, v7
	v_fmac_f32_e32 v4, v3, v3
	v_lshlrev_b32_e32 v3, 16, v7
	v_mul_f32_e32 v5, v5, v5
	v_fmac_f32_e32 v5, v3, v3
	v_add_f32_e32 v3, v4, v5
	v_and_b32_e32 v5, 0xffff0000, v8
	v_lshlrev_b32_e32 v4, 16, v8
	v_mul_f32_e32 v5, v5, v5
	v_fmac_f32_e32 v5, v4, v4
	v_add_f32_e32 v3, v5, v3
	v_and_b32_e32 v5, 0xffff0000, v9
	v_add_f32_e32 v2, v14, v2
	v_lshlrev_b32_e32 v4, 16, v9
	v_mul_f32_e32 v5, v5, v5
	v_fmac_f32_e32 v5, v4, v4
	ds_bpermute_b32 v4, v235, v2
	v_add_f32_e32 v3, v5, v3
	v_add_f32_e32 v3, v15, v3
	v_mad_i64_i32 v[6:7], s[0:1], s24, v230, v[84:85]
	s_waitcnt lgkmcnt(0)
	v_add_f32_e32 v2, v2, v4
	ds_bpermute_b32 v4, v236, v2
	v_add_co_u32_e32 v18, vcc, s3, v6
	s_waitcnt lgkmcnt(0)
	v_add_f32_e32 v10, v2, v4
	ds_bpermute_b32 v2, v235, v3
	v_addc_co_u32_e32 v19, vcc, 0, v7, vcc
	v_add_co_u32_e32 v6, vcc, s89, v6
	s_waitcnt lgkmcnt(0)
	v_add_f32_e32 v2, v3, v2
	ds_bpermute_b32 v3, v236, v2
	v_addc_co_u32_e32 v7, vcc, 0, v7, vcc
	v_mov_b32_e32 v14, v134
	v_mov_b32_e32 v15, v135
	v_mov_b32_e32 v16, v136
	v_mov_b32_e32 v17, v137
	ds_bpermute_b32 v11, v237, v10
	s_waitcnt lgkmcnt(0)
	v_add_f32_e32 v12, v2, v3
	v_mov_b32_e32 v2, v126
	v_mov_b32_e32 v3, v127
	v_mov_b32_e32 v4, v128
	v_mov_b32_e32 v5, v129
	ds_bpermute_b32 v13, v237, v12
	s_waitcnt lgkmcnt(0)
; __device__ __forceinline__ void preproc_phase(Frame& F, int layer, int b, int cu_lo, int ncu) {
;     ...
;         {   float mq2 = 0.f, mk2 = 0.f;
; #pragma unroll
;             for (int a = 0; a < 4; ++a) { const bf16_t* rp = proj + (size_t)(t0 + a) * NP + c0; float sq = 0.f, sk = 0.f;
; #pragma unroll
;                 for (int hf = 0; hf < 2; ++hf) { const u32x4 qv = *(const u32x4*)(rp + C_FQ + 8 * hf), kv = *(const u32x4*)(rp + C_FK + 8 * hf);
;                     sq += (bflo(qv.x) * bflo(qv.x) + bfhi(qv.x) * bfhi(qv.x)) + (bflo(qv.y) * bflo(qv.y) + bfhi(qv.y) * bfhi(qv.y)) + (bflo(qv.z) * bflo(qv.z) + bfhi(qv.z) * bfhi(qv.z)) + (bflo(qv.w) * bflo(qv.w) + bfhi(qv.w) * bfhi(qv.w));
;                     sk += (bflo(kv.x) * bflo(kv.x) + bfhi(kv.x) * bfhi(kv.x)) + (bflo(kv.y) * bflo(kv.y) + bfhi(kv.y) * bfhi(kv.y)) + (bflo(kv.z) * bflo(kv.z) + bfhi(kv.z) * bfhi(kv.z)) + (bflo(kv.w) * bflo(kv.w) + bfhi(kv.w) * bfhi(kv.w)); }
;                 sq += __shfl_xor(sq, 1); sq += __shfl_xor(sq, 2); sq += __shfl_xor(sq, 4); sk += __shfl_xor(sk, 1); sk += __shfl_xor(sk, 2); sk += __shfl_xor(sk, 4);
;                 mq2 = fmaxf(mq2, sq); mk2 = fmaxf(mk2, sk); }
;             if ((F.lane & 7) == 0) { atomicMax(nrm, __builtin_bit_cast(unsigned, mq2 * 1.001f)); atomicMax(nrm + 8, __builtin_bit_cast(unsigned, mk2 * 1.001f)); } }
	v_lshlrev_b32_e32 v8, 16, v2
	v_and_b32_e32 v2, 0xffff0000, v2
	v_mul_f32_e32 v2, v2, v2
	v_fmac_f32_e32 v2, v8, v8
	v_lshlrev_b32_e32 v8, 16, v3
	v_and_b32_e32 v3, 0xffff0000, v3
	v_mul_f32_e32 v3, v3, v3
	v_fmac_f32_e32 v3, v8, v8
	v_add_f32_e32 v2, v2, v3
	v_lshlrev_b32_e32 v3, 16, v4
	v_and_b32_e32 v4, 0xffff0000, v4
	v_mul_f32_e32 v4, v4, v4
	v_fmac_f32_e32 v4, v3, v3
	v_add_f32_e32 v2, v4, v2
	v_and_b32_e32 v4, 0xffff0000, v5
	v_lshlrev_b32_e32 v3, 16, v5
	v_mul_f32_e32 v4, v4, v4
	v_fmac_f32_e32 v4, v3, v3
	v_and_b32_e32 v3, 0xffff0000, v14
	v_add_f32_e32 v9, v4, v2
	v_lshlrev_b32_e32 v2, 16, v14
	v_mul_f32_e32 v3, v3, v3
	v_and_b32_e32 v4, 0xffff0000, v15
	v_fmac_f32_e32 v3, v2, v2
	v_lshlrev_b32_e32 v2, 16, v15
	v_mul_f32_e32 v4, v4, v4
	v_fmac_f32_e32 v4, v2, v2
	v_add_f32_e32 v2, v3, v4
	v_and_b32_e32 v4, 0xffff0000, v16
	v_lshlrev_b32_e32 v3, 16, v16
	v_mul_f32_e32 v4, v4, v4
	v_fmac_f32_e32 v4, v3, v3
	v_add_f32_e32 v2, v4, v2
	v_and_b32_e32 v4, 0xffff0000, v17
	v_lshlrev_b32_e32 v3, 16, v17
	v_mul_f32_e32 v4, v4, v4
	v_fmac_f32_e32 v4, v3, v3
	v_add_f32_e32 v8, v4, v2
	v_mov_b32_e32 v2, v130
	v_mov_b32_e32 v3, v131
	v_mov_b32_e32 v4, v132
	v_mov_b32_e32 v5, v133
	v_mov_b32_e32 v14, v138
	v_mov_b32_e32 v15, v139
	v_mov_b32_e32 v16, v140
	v_mov_b32_e32 v17, v141
	s_waitcnt lgkmcnt(0)
	v_lshlrev_b32_e32 v6, 16, v2
	v_and_b32_e32 v2, 0xffff0000, v2
	v_mul_f32_e32 v2, v2, v2
	v_fmac_f32_e32 v2, v6, v6
	v_lshlrev_b32_e32 v6, 16, v3
	v_and_b32_e32 v3, 0xffff0000, v3
	v_mul_f32_e32 v3, v3, v3
	v_fmac_f32_e32 v3, v6, v6
	v_add_f32_e32 v2, v2, v3
	v_lshlrev_b32_e32 v3, 16, v4
	v_and_b32_e32 v4, 0xffff0000, v4
	v_mul_f32_e32 v4, v4, v4
	v_fmac_f32_e32 v4, v3, v3
	v_add_f32_e32 v2, v4, v2
	v_and_b32_e32 v4, 0xffff0000, v5
	v_lshlrev_b32_e32 v3, 16, v5
	v_mul_f32_e32 v4, v4, v4
	v_fmac_f32_e32 v4, v3, v3
	v_add_f32_e32 v2, v4, v2
	v_and_b32_e32 v4, 0xffff0000, v14
	v_lshlrev_b32_e32 v3, 16, v14
	v_mul_f32_e32 v4, v4, v4
	v_and_b32_e32 v5, 0xffff0000, v15
	v_fmac_f32_e32 v4, v3, v3
	v_lshlrev_b32_e32 v3, 16, v15
	v_mul_f32_e32 v5, v5, v5
	v_fmac_f32_e32 v5, v3, v3
	v_add_f32_e32 v3, v4, v5
	v_and_b32_e32 v5, 0xffff0000, v16
	v_lshlrev_b32_e32 v4, 16, v16
	v_mul_f32_e32 v5, v5, v5
	v_fmac_f32_e32 v5, v4, v4
	v_add_f32_e32 v3, v5, v3
	v_and_b32_e32 v5, 0xffff0000, v17
	v_add_f32_e32 v2, v9, v2
	v_lshlrev_b32_e32 v4, 16, v17
	v_mul_f32_e32 v5, v5, v5
	v_fmac_f32_e32 v5, v4, v4
	ds_bpermute_b32 v4, v235, v2
	v_add_f32_e32 v3, v5, v3
	v_add_f32_e32 v3, v8, v3
	s_waitcnt lgkmcnt(0)
	v_add_f32_e32 v2, v2, v4
	ds_bpermute_b32 v4, v236, v2
	s_waitcnt lgkmcnt(0)
	v_add_f32_e32 v14, v2, v4
	ds_bpermute_b32 v2, v235, v3
	v_mad_i64_i32 v[4:5], s[0:1], s22, v230, v[84:85]
	ds_bpermute_b32 v15, v237, v14
	s_waitcnt lgkmcnt(1)
	v_add_f32_e32 v2, v3, v2
	ds_bpermute_b32 v3, v236, v2
	s_waitcnt lgkmcnt(0)
	v_add_f32_e32 v16, v2, v3
	v_add_co_u32_e32 v2, vcc, s3, v4
	ds_bpermute_b32 v17, v237, v16
	s_nop 0
	v_addc_co_u32_e32 v3, vcc, 0, v5, vcc
	v_mov_b32_e32 v6, v186
	v_mov_b32_e32 v7, v187
	v_mov_b32_e32 v8, v188
	v_mov_b32_e32 v9, v189
	v_add_co_u32_e32 v4, vcc, s89, v4
	s_nop 1
	v_addc_co_u32_e32 v5, vcc, 0, v5, vcc
	v_mov_b32_e32 v18, v194
	v_mov_b32_e32 v19, v195
	v_mov_b32_e32 v20, v196
	v_mov_b32_e32 v21, v197
	s_waitcnt lgkmcnt(0)
	v_lshlrev_b32_e32 v22, 16, v6
	v_and_b32_e32 v6, 0xffff0000, v6
	v_mul_f32_e32 v6, v6, v6
	v_fmac_f32_e32 v6, v22, v22
	v_lshlrev_b32_e32 v22, 16, v7
	v_and_b32_e32 v7, 0xffff0000, v7
	v_mul_f32_e32 v7, v7, v7
	v_fmac_f32_e32 v7, v22, v22
	v_add_f32_e32 v6, v6, v7
	v_lshlrev_b32_e32 v7, 16, v8
	v_and_b32_e32 v8, 0xffff0000, v8
	v_mul_f32_e32 v8, v8, v8
	v_fmac_f32_e32 v8, v7, v7
	v_add_f32_e32 v6, v8, v6
	v_and_b32_e32 v8, 0xffff0000, v9
	v_lshlrev_b32_e32 v7, 16, v9
	v_mul_f32_e32 v8, v8, v8
	v_fmac_f32_e32 v8, v7, v7
	v_and_b32_e32 v7, 0xffff0000, v18
	v_add_f32_e32 v22, v8, v6
	v_lshlrev_b32_e32 v6, 16, v18
	v_mul_f32_e32 v7, v7, v7
	v_and_b32_e32 v8, 0xffff0000, v19
	v_fmac_f32_e32 v7, v6, v6
	v_lshlrev_b32_e32 v6, 16, v19
	v_mul_f32_e32 v8, v8, v8
	v_fmac_f32_e32 v8, v6, v6
	v_add_f32_e32 v6, v7, v8
	v_and_b32_e32 v8, 0xffff0000, v20
	v_lshlrev_b32_e32 v7, 16, v20
	v_mul_f32_e32 v8, v8, v8
	v_fmac_f32_e32 v8, v7, v7
	v_add_f32_e32 v6, v8, v6
	v_and_b32_e32 v8, 0xffff0000, v21
	v_lshlrev_b32_e32 v7, 16, v21
	v_mul_f32_e32 v8, v8, v8
	v_fmac_f32_e32 v8, v7, v7
	v_add_f32_e32 v18, v8, v6
	v_mov_b32_e32 v6, v190
	v_mov_b32_e32 v7, v191
	v_mov_b32_e32 v8, v192
	v_mov_b32_e32 v9, v193
	s_nop 0
	v_mov_b32_e32 v2, v198
	v_mov_b32_e32 v3, v199
	v_mov_b32_e32 v4, v200
	v_mov_b32_e32 v5, v201
	s_waitcnt lgkmcnt(0)
; __device__ __forceinline__ void preproc_phase(Frame& F, int layer, int b, int cu_lo, int ncu) {
;     ...
;         {   float mq2 = 0.f, mk2 = 0.f;
; #pragma unroll
;             for (int a = 0; a < 4; ++a) { const bf16_t* rp = proj + (size_t)(t0 + a) * NP + c0; float sq = 0.f, sk = 0.f;
; #pragma unroll
;                 for (int hf = 0; hf < 2; ++hf) { const u32x4 qv = *(const u32x4*)(rp + C_FQ + 8 * hf), kv = *(const u32x4*)(rp + C_FK + 8 * hf);
;                     sq += (bflo(qv.x) * bflo(qv.x) + bfhi(qv.x) * bfhi(qv.x)) + (bflo(qv.y) * bflo(qv.y) + bfhi(qv.y) * bfhi(qv.y)) + (bflo(qv.z) * bflo(qv.z) + bfhi(qv.z) * bfhi(qv.z)) + (bflo(qv.w) * bflo(qv.w) + bfhi(qv.w) * bfhi(qv.w));
;                     sk += (bflo(kv.x) * bflo(kv.x) + bfhi(kv.x) * bfhi(kv.x)) + (bflo(kv.y) * bflo(kv.y) + bfhi(kv.y) * bfhi(kv.y)) + (bflo(kv.z) * bflo(kv.z) + bfhi(kv.z) * bfhi(kv.z)) + (bflo(kv.w) * bflo(kv.w) + bfhi(kv.w) * bfhi(kv.w)); }
;                 sq += __shfl_xor(sq, 1); sq += __shfl_xor(sq, 2); sq += __shfl_xor(sq, 4); sk += __shfl_xor(sk, 1); sk += __shfl_xor(sk, 2); sk += __shfl_xor(sk, 4);
;                 mq2 = fmaxf(mq2, sq); mk2 = fmaxf(mk2, sk); }
;             if ((F.lane & 7) == 0) { atomicMax(nrm, __builtin_bit_cast(unsigned, mq2 * 1.001f)); atomicMax(nrm + 8, __builtin_bit_cast(unsigned, mk2 * 1.001f)); } }
	v_lshlrev_b32_e32 v19, 16, v6
	v_and_b32_e32 v6, 0xffff0000, v6
	v_mul_f32_e32 v6, v6, v6
	v_fmac_f32_e32 v6, v19, v19
	v_lshlrev_b32_e32 v19, 16, v7
	v_and_b32_e32 v7, 0xffff0000, v7
	v_mul_f32_e32 v7, v7, v7
	v_fmac_f32_e32 v7, v19, v19
	v_add_f32_e32 v6, v6, v7
	v_lshlrev_b32_e32 v7, 16, v8
	v_and_b32_e32 v8, 0xffff0000, v8
	v_mul_f32_e32 v8, v8, v8
	v_fmac_f32_e32 v8, v7, v7
	v_add_f32_e32 v6, v8, v6
	v_and_b32_e32 v8, 0xffff0000, v9
	v_lshlrev_b32_e32 v7, 16, v9
	v_mul_f32_e32 v8, v8, v8
	v_fmac_f32_e32 v8, v7, v7
	v_lshlrev_b32_e32 v7, 16, v2
	v_and_b32_e32 v2, 0xffff0000, v2
	v_mul_f32_e32 v2, v2, v2
	v_fmac_f32_e32 v2, v7, v7
	v_lshlrev_b32_e32 v7, 16, v3
	v_and_b32_e32 v3, 0xffff0000, v3
	v_mul_f32_e32 v3, v3, v3
	v_fmac_f32_e32 v3, v7, v7
	v_add_f32_e32 v2, v2, v3
	v_lshlrev_b32_e32 v3, 16, v4
	v_and_b32_e32 v4, 0xffff0000, v4
	v_mul_f32_e32 v4, v4, v4
	v_fmac_f32_e32 v4, v3, v3
	v_add_f32_e32 v6, v8, v6
	v_add_f32_e32 v2, v4, v2
	v_and_b32_e32 v4, 0xffff0000, v5
	v_add_f32_e32 v6, v22, v6
	v_lshlrev_b32_e32 v3, 16, v5
	v_mul_f32_e32 v4, v4, v4
	v_fmac_f32_e32 v4, v3, v3
	ds_bpermute_b32 v3, v235, v6
	v_add_f32_e32 v2, v4, v2
	v_add_f32_e32 v2, v18, v2
	s_waitcnt lgkmcnt(0)
	v_add_f32_e32 v3, v6, v3
	ds_bpermute_b32 v4, v236, v3
	s_waitcnt lgkmcnt(0)
	v_add_f32_e32 v18, v3, v4
	ds_bpermute_b32 v3, v235, v2
	v_mad_i64_i32 v[4:5], s[0:1], s20, v230, v[84:85]
	ds_bpermute_b32 v19, v237, v18
	s_waitcnt lgkmcnt(1)
	v_add_f32_e32 v2, v2, v3
	ds_bpermute_b32 v3, v236, v2
	s_waitcnt lgkmcnt(0)
	v_add_f32_e32 v20, v2, v3
	v_add_co_u32_e32 v2, vcc, s3, v4
	ds_bpermute_b32 v21, v237, v20
	s_nop 0
	v_addc_co_u32_e32 v3, vcc, 0, v5, vcc
	v_mov_b32_e32 v22, v202
	v_mov_b32_e32 v23, v203
	v_mov_b32_e32 v24, v204
	v_mov_b32_e32 v25, v205
	v_add_co_u32_e32 v6, vcc, s89, v4
	s_nop 1
	v_addc_co_u32_e32 v7, vcc, 0, v5, vcc
	v_mov_b32_e32 v26, v210
	v_mov_b32_e32 v27, v211
	v_mov_b32_e32 v28, v212
	v_mov_b32_e32 v29, v213
	s_waitcnt lgkmcnt(0)
	v_and_b32_e32 v5, 0xffff0000, v22
	v_lshlrev_b32_e32 v4, 16, v22
	v_mul_f32_e32 v5, v5, v5
	v_and_b32_e32 v8, 0xffff0000, v23
	v_fmac_f32_e32 v5, v4, v4
	v_lshlrev_b32_e32 v4, 16, v23
	v_mul_f32_e32 v8, v8, v8
	v_fmac_f32_e32 v8, v4, v4
	v_add_f32_e32 v4, v5, v8
	v_and_b32_e32 v8, 0xffff0000, v24
	v_lshlrev_b32_e32 v5, 16, v24
	v_mul_f32_e32 v8, v8, v8
	v_fmac_f32_e32 v8, v5, v5
	v_add_f32_e32 v4, v8, v4
	v_and_b32_e32 v8, 0xffff0000, v25
	v_lshlrev_b32_e32 v5, 16, v25
	v_mul_f32_e32 v8, v8, v8
	v_fmac_f32_e32 v8, v5, v5
	v_and_b32_e32 v5, 0xffff0000, v26
	v_add_f32_e32 v23, v8, v4
	v_lshlrev_b32_e32 v4, 16, v26
	v_mul_f32_e32 v5, v5, v5
	v_and_b32_e32 v8, 0xffff0000, v27
	v_fmac_f32_e32 v5, v4, v4
	v_lshlrev_b32_e32 v4, 16, v27
	v_mul_f32_e32 v8, v8, v8
	v_fmac_f32_e32 v8, v4, v4
	v_add_f32_e32 v4, v5, v8
	v_and_b32_e32 v8, 0xffff0000, v28
	v_lshlrev_b32_e32 v5, 16, v28
	v_mul_f32_e32 v8, v8, v8
	v_fmac_f32_e32 v8, v5, v5
	v_add_f32_e32 v4, v8, v4
	v_and_b32_e32 v8, 0xffff0000, v29
	v_lshlrev_b32_e32 v5, 16, v29
	v_mul_f32_e32 v8, v8, v8
	v_fmac_f32_e32 v8, v5, v5
	v_add_f32_e32 v22, v8, v4
	v_mov_b32_e32 v2, v206
	v_mov_b32_e32 v3, v207
	v_mov_b32_e32 v4, v208
	v_mov_b32_e32 v5, v209
	s_nop 0
	v_mov_b32_e32 v6, v214
	v_mov_b32_e32 v7, v215
	v_mov_b32_e32 v8, v216
	v_mov_b32_e32 v9, v217
	s_waitcnt lgkmcnt(0)
	v_lshlrev_b32_e32 v24, 16, v2
	v_and_b32_e32 v2, 0xffff0000, v2
	v_mul_f32_e32 v2, v2, v2
	v_fmac_f32_e32 v2, v24, v24
	v_lshlrev_b32_e32 v24, 16, v3
	v_and_b32_e32 v3, 0xffff0000, v3
	v_mul_f32_e32 v3, v3, v3
	v_fmac_f32_e32 v3, v24, v24
	v_add_f32_e32 v2, v2, v3
	v_lshlrev_b32_e32 v3, 16, v4
	v_and_b32_e32 v4, 0xffff0000, v4
	v_mul_f32_e32 v4, v4, v4
	v_fmac_f32_e32 v4, v3, v3
	v_add_f32_e32 v2, v4, v2
	v_and_b32_e32 v4, 0xffff0000, v5
	v_lshlrev_b32_e32 v3, 16, v5
	v_mul_f32_e32 v4, v4, v4
	v_fmac_f32_e32 v4, v3, v3
	v_add_f32_e32 v2, v4, v2
	v_and_b32_e32 v4, 0xffff0000, v6
	v_lshlrev_b32_e32 v3, 16, v6
	v_mul_f32_e32 v4, v4, v4
	v_and_b32_e32 v5, 0xffff0000, v7
	v_fmac_f32_e32 v4, v3, v3
	v_lshlrev_b32_e32 v3, 16, v7
	v_mul_f32_e32 v5, v5, v5
	v_fmac_f32_e32 v5, v3, v3
	v_add_f32_e32 v3, v4, v5
	v_and_b32_e32 v5, 0xffff0000, v8
	v_lshlrev_b32_e32 v4, 16, v8
	v_mul_f32_e32 v5, v5, v5
	v_fmac_f32_e32 v5, v4, v4
	v_add_f32_e32 v3, v5, v3
	v_and_b32_e32 v5, 0xffff0000, v9
	v_lshlrev_b32_e32 v4, 16, v9
	v_mul_f32_e32 v5, v5, v5
	v_fmac_f32_e32 v5, v4, v4
	v_add_f32_e32 v3, v5, v3
	v_add_f32_e32 v2, v23, v2
	v_add_f32_e32 v4, v22, v3
	ds_bpermute_b32 v3, v235, v2
	ds_bpermute_b32 v5, v235, v4
	s_waitcnt lgkmcnt(1)
	v_add_f32_e32 v2, v2, v3
	s_waitcnt lgkmcnt(0)
	v_add_f32_e32 v4, v4, v5
	ds_bpermute_b32 v3, v236, v2
	ds_bpermute_b32 v5, v236, v4
	s_waitcnt lgkmcnt(1)
	v_add_f32_e32 v2, v2, v3
	s_waitcnt lgkmcnt(0)
	v_add_f32_e32 v4, v4, v5
	ds_bpermute_b32 v3, v237, v2
	ds_bpermute_b32 v5, v237, v4
	s_and_saveexec_b64 s[0:1], s[6:7]
	s_cbranch_execz .LBB0_297
	v_add_f32_e32 v6, v12, v13
	v_add_f32_e32 v7, v16, v17
	v_max3_f32 v6, v6, 0, v7
	v_add_f32_e32 v7, v20, v21
	s_waitcnt lgkmcnt(0)
	v_add_f32_e32 v4, v4, v5
	v_max3_f32 v4, v6, v7, v4
	v_add_f32_e32 v5, v10, v11
	v_add_f32_e32 v6, v14, v15
	v_max3_f32 v5, v5, 0, v6
	v_add_f32_e32 v6, v18, v19
	v_add_f32_e32 v2, v2, v3
	v_max3_f32 v2, v5, v6, v2
	v_mul_f32_e32 v2, 0x3f8020c5, v2
	v_mul_f32_e32 v3, 0x3f8020c5, v4
	flat_atomic_umax v[82:83], v2
	flat_atomic_umax v[82:83], v3 offset:32

; __device__ __forceinline__ void preproc_phase(Frame& F, int layer, int b, int cu_lo, int ncu) {
;     ...
;         {   float mq2 = 0.f, mk2 = 0.f;
; #pragma unroll
;             for (int a = 0; a < 4; ++a) { const bf16_t* rp = proj + (size_t)(t0 + a) * NP + c0; float sq = 0.f, sk = 0.f;
; #pragma unroll
;                 for (int hf = 0; hf < 2; ++hf) { const u32x4 qv = *(const u32x4*)(rp + C_FQ + 8 * hf), kv = *(const u32x4*)(rp + C_FK + 8 * hf);
;                     sq += (bflo(qv.x) * bflo(qv.x) + bfhi(qv.x) * bfhi(qv.x)) + (bflo(qv.y) * bflo(qv.y) + bfhi(qv.y) * bfhi(qv.y)) + (bflo(qv.z) * bflo(qv.z) + bfhi(qv.z) * bfhi(qv.z)) + (bflo(qv.w) * bflo(qv.w) + bfhi(qv.w) * bfhi(qv.w));
;                     sk += (bflo(kv.x) * bflo(kv.x) + bfhi(kv.x) * bfhi(kv.x)) + (bflo(kv.y) * bflo(kv.y) + bfhi(kv.y) * bfhi(kv.y)) + (bflo(kv.z) * bflo(kv.z) + bfhi(kv.z) * bfhi(kv.z)) + (bflo(kv.w) * bflo(kv.w) + bfhi(kv.w) * bfhi(kv.w)); }
;                 sq += __shfl_xor(sq, 1); sq += __shfl_xor(sq, 2); sq += __shfl_xor(sq, 4); sk += __shfl_xor(sk, 1); sk += __shfl_xor(sk, 2); sk += __shfl_xor(sk, 4);
;                 mq2 = fmaxf(mq2, sq); mk2 = fmaxf(mk2, sk); }
;             if ((F.lane & 7) == 0) { atomicMax(nrm, __builtin_bit_cast(unsigned, mq2 * 1.001f)); atomicMax(nrm + 8, __builtin_bit_cast(unsigned, mk2 * 1.001f)); } }
.LBB0_323:
	s_lshl_b32 s26, s48, 2
	v_mad_i64_i32 v[6:7], s[0:1], s26, v230, v[86:87]
	s_or_b32 s24, s26, 1
	s_or_b32 s22, s26, 2
	s_or_b32 s20, s26, 3
	v_mad_i64_i32 v[178:179], s[0:1], s24, v230, v[86:87]
	v_mad_i64_i32 v[180:181], s[0:1], s22, v230, v[86:87]
	v_mad_i64_i32 v[182:183], s[0:1], s20, v230, v[86:87]
	v_add_co_u32_e32 v184, vcc, 0x2800, v6
	s_nop 1
	v_addc_co_u32_e32 v185, vcc, 0, v7, vcc
	global_load_dwordx4 v[110:113], v[184:185], off
	global_load_dwordx4 v[114:117], v[184:185], off offset:16
	global_load_dwordx4 v[118:121], v[184:185], off offset:2048
	global_load_dwordx4 v[122:125], v[184:185], off offset:2064
	v_add_co_u32_e32 v184, vcc, 0x2800, v178
	s_nop 1
	v_addc_co_u32_e32 v185, vcc, 0, v179, vcc
	global_load_dwordx4 v[126:129], v[184:185], off
	global_load_dwordx4 v[130:133], v[184:185], off offset:16
	global_load_dwordx4 v[134:137], v[184:185], off offset:2048
	global_load_dwordx4 v[138:141], v[184:185], off offset:2064
	v_add_co_u32_e32 v184, vcc, 0x2800, v180
	s_nop 1
	v_addc_co_u32_e32 v185, vcc, 0, v181, vcc
	global_load_dwordx4 v[186:189], v[184:185], off
	global_load_dwordx4 v[190:193], v[184:185], off offset:16
	global_load_dwordx4 v[194:197], v[184:185], off offset:2048
	global_load_dwordx4 v[198:201], v[184:185], off offset:2064
	v_add_co_u32_e32 v184, vcc, 0x2800, v182
	s_nop 1
	v_addc_co_u32_e32 v185, vcc, 0, v183, vcc
	global_load_dwordx4 v[202:205], v[184:185], off
	global_load_dwordx4 v[206:209], v[184:185], off offset:16
	global_load_dwordx4 v[210:213], v[184:185], off offset:2048
	global_load_dwordx4 v[214:217], v[184:185], off offset:2064
	v_add_co_u32_e32 v10, vcc, 0x2000, v6
	s_or_b32 s24, s26, 1
	s_nop 0
	v_addc_co_u32_e32 v11, vcc, 0, v7, vcc
	v_mov_b32_e32 v2, v110
	v_mov_b32_e32 v3, v111
	v_mov_b32_e32 v4, v112
	v_mov_b32_e32 v5, v113
	v_add_co_u32_e32 v12, vcc, 0x3000, v6
	s_or_b32 s22, s26, 2
	s_nop 0
	v_addc_co_u32_e32 v13, vcc, 0, v7, vcc
	v_mov_b32_e32 v6, v118
	v_mov_b32_e32 v7, v119
	v_mov_b32_e32 v8, v120
	v_mov_b32_e32 v9, v121
	s_or_b32 s20, s26, 3
	s_waitcnt vmcnt(0) lgkmcnt(0)
	v_lshlrev_b32_e32 v14, 16, v2
	v_and_b32_e32 v2, 0xffff0000, v2
	v_mul_f32_e32 v2, v2, v2
	v_fmac_f32_e32 v2, v14, v14
	v_lshlrev_b32_e32 v14, 16, v3
	v_and_b32_e32 v3, 0xffff0000, v3
	v_mul_f32_e32 v3, v3, v3
	v_fmac_f32_e32 v3, v14, v14
	v_add_f32_e32 v2, v2, v3
	v_lshlrev_b32_e32 v3, 16, v4
	v_and_b32_e32 v4, 0xffff0000, v4
	v_mul_f32_e32 v4, v4, v4
	v_fmac_f32_e32 v4, v3, v3
	v_add_f32_e32 v2, v4, v2
	v_and_b32_e32 v4, 0xffff0000, v5
	v_lshlrev_b32_e32 v3, 16, v5
	v_mul_f32_e32 v4, v4, v4
	v_fmac_f32_e32 v4, v3, v3
	v_and_b32_e32 v3, 0xffff0000, v6
	v_add_f32_e32 v14, v4, v2
	v_lshlrev_b32_e32 v2, 16, v6
	v_mul_f32_e32 v3, v3, v3
	v_and_b32_e32 v4, 0xffff0000, v7
	v_fmac_f32_e32 v3, v2, v2
	v_lshlrev_b32_e32 v2, 16, v7
	v_mul_f32_e32 v4, v4, v4
	v_fmac_f32_e32 v4, v2, v2
	v_add_f32_e32 v2, v3, v4
	v_and_b32_e32 v4, 0xffff0000, v8
	v_lshlrev_b32_e32 v3, 16, v8
	v_mul_f32_e32 v4, v4, v4
	v_fmac_f32_e32 v4, v3, v3
	v_add_f32_e32 v2, v4, v2
	v_and_b32_e32 v4, 0xffff0000, v9
	v_lshlrev_b32_e32 v3, 16, v9
	v_mul_f32_e32 v4, v4, v4
	v_fmac_f32_e32 v4, v3, v3
	v_add_f32_e32 v15, v4, v2
	v_mov_b32_e32 v2, v114
	v_mov_b32_e32 v3, v115
	v_mov_b32_e32 v4, v116
	v_mov_b32_e32 v5, v117
	v_mov_b32_e32 v6, v122
	v_mov_b32_e32 v7, v123
	v_mov_b32_e32 v8, v124
	v_mov_b32_e32 v9, v125
	s_waitcnt lgkmcnt(0)
	v_lshlrev_b32_e32 v10, 16, v2
	v_and_b32_e32 v2, 0xffff0000, v2
	v_mul_f32_e32 v2, v2, v2
	v_fmac_f32_e32 v2, v10, v10
	v_lshlrev_b32_e32 v10, 16, v3
	v_and_b32_e32 v3, 0xffff0000, v3
	v_mul_f32_e32 v3, v3, v3
	v_fmac_f32_e32 v3, v10, v10
	v_add_f32_e32 v2, v2, v3
	v_lshlrev_b32_e32 v3, 16, v4
	v_and_b32_e32 v4, 0xffff0000, v4
	v_mul_f32_e32 v4, v4, v4
	v_fmac_f32_e32 v4, v3, v3
	v_add_f32_e32 v2, v4, v2
	v_and_b32_e32 v4, 0xffff0000, v5
	v_lshlrev_b32_e32 v3, 16, v5
	v_mul_f32_e32 v4, v4, v4
	v_fmac_f32_e32 v4, v3, v3
	v_add_f32_e32 v2, v4, v2
	v_and_b32_e32 v4, 0xffff0000, v6
	v_lshlrev_b32_e32 v3, 16, v6
	v_mul_f32_e32 v4, v4, v4
	v_and_b32_e32 v5, 0xffff0000, v7
	v_fmac_f32_e32 v4, v3, v3
	v_lshlrev_b32_e32 v3, 16, v7
	v_mul_f32_e32 v5, v5, v5
	v_fmac_f32_e32 v5, v3, v3
	v_add_f32_e32 v3, v4, v5
	v_and_b32_e32 v5, 0xffff0000, v8
	v_lshlrev_b32_e32 v4, 16, v8
	v_mul_f32_e32 v5, v5, v5
	v_fmac_f32_e32 v5, v4, v4
	v_add_f32_e32 v3, v5, v3
	v_and_b32_e32 v5, 0xffff0000, v9
	v_add_f32_e32 v2, v14, v2
	v_lshlrev_b32_e32 v4, 16, v9
	v_mul_f32_e32 v5, v5, v5
	v_fmac_f32_e32 v5, v4, v4
	ds_bpermute_b32 v4, v235, v2
	v_add_f32_e32 v3, v5, v3
	v_add_f32_e32 v3, v15, v3
	v_mad_i64_i32 v[6:7], s[0:1], s24, v230, v[86:87]
	s_waitcnt lgkmcnt(0)
	v_add_f32_e32 v2, v2, v4
	ds_bpermute_b32 v4, v236, v2
	v_add_co_u32_e32 v18, vcc, s3, v6
	s_waitcnt lgkmcnt(0)
	v_add_f32_e32 v10, v2, v4
	ds_bpermute_b32 v2, v235, v3
	v_addc_co_u32_e32 v19, vcc, 0, v7, vcc
	v_add_co_u32_e32 v6, vcc, s89, v6
	s_waitcnt lgkmcnt(0)
	v_add_f32_e32 v2, v3, v2
	ds_bpermute_b32 v3, v236, v2
	v_addc_co_u32_e32 v7, vcc, 0, v7, vcc
	v_mov_b32_e32 v14, v134
	v_mov_b32_e32 v15, v135
	v_mov_b32_e32 v16, v136
	v_mov_b32_e32 v17, v137
	ds_bpermute_b32 v11, v237, v10
	s_waitcnt lgkmcnt(0)
	v_add_f32_e32 v12, v2, v3
	v_mov_b32_e32 v2, v126
	v_mov_b32_e32 v3, v127
	v_mov_b32_e32 v4, v128
	v_mov_b32_e32 v5, v129
	ds_bpermute_b32 v13, v237, v12
	s_waitcnt lgkmcnt(0)
; __device__ __forceinline__ void preproc_phase(Frame& F, int layer, int b, int cu_lo, int ncu) {
;     ...
;         {   float mq2 = 0.f, mk2 = 0.f;
; #pragma unroll
;             for (int a = 0; a < 4; ++a) { const bf16_t* rp = proj + (size_t)(t0 + a) * NP + c0; float sq = 0.f, sk = 0.f;
; #pragma unroll
;                 for (int hf = 0; hf < 2; ++hf) { const u32x4 qv = *(const u32x4*)(rp + C_FQ + 8 * hf), kv = *(const u32x4*)(rp + C_FK + 8 * hf);
;                     sq += (bflo(qv.x) * bflo(qv.x) + bfhi(qv.x) * bfhi(qv.x)) + (bflo(qv.y) * bflo(qv.y) + bfhi(qv.y) * bfhi(qv.y)) + (bflo(qv.z) * bflo(qv.z) + bfhi(qv.z) * bfhi(qv.z)) + (bflo(qv.w) * bflo(qv.w) + bfhi(qv.w) * bfhi(qv.w));
;                     sk += (bflo(kv.x) * bflo(kv.x) + bfhi(kv.x) * bfhi(kv.x)) + (bflo(kv.y) * bflo(kv.y) + bfhi(kv.y) * bfhi(kv.y)) + (bflo(kv.z) * bflo(kv.z) + bfhi(kv.z) * bfhi(kv.z)) + (bflo(kv.w) * bflo(kv.w) + bfhi(kv.w) * bfhi(kv.w)); }
;                 sq += __shfl_xor(sq, 1); sq += __shfl_xor(sq, 2); sq += __shfl_xor(sq, 4); sk += __shfl_xor(sk, 1); sk += __shfl_xor(sk, 2); sk += __shfl_xor(sk, 4);
;                 mq2 = fmaxf(mq2, sq); mk2 = fmaxf(mk2, sk); }
;             if ((F.lane & 7) == 0) { atomicMax(nrm, __builtin_bit_cast(unsigned, mq2 * 1.001f)); atomicMax(nrm + 8, __builtin_bit_cast(unsigned, mk2 * 1.001f)); } }
	v_lshlrev_b32_e32 v8, 16, v2
	v_and_b32_e32 v2, 0xffff0000, v2
	v_mul_f32_e32 v2, v2, v2
	v_fmac_f32_e32 v2, v8, v8
	v_lshlrev_b32_e32 v8, 16, v3
	v_and_b32_e32 v3, 0xffff0000, v3
	v_mul_f32_e32 v3, v3, v3
	v_fmac_f32_e32 v3, v8, v8
	v_add_f32_e32 v2, v2, v3
	v_lshlrev_b32_e32 v3, 16, v4
	v_and_b32_e32 v4, 0xffff0000, v4
	v_mul_f32_e32 v4, v4, v4
	v_fmac_f32_e32 v4, v3, v3
	v_add_f32_e32 v2, v4, v2
	v_and_b32_e32 v4, 0xffff0000, v5
	v_lshlrev_b32_e32 v3, 16, v5
	v_mul_f32_e32 v4, v4, v4
	v_fmac_f32_e32 v4, v3, v3
	v_and_b32_e32 v3, 0xffff0000, v14
	v_add_f32_e32 v9, v4, v2
	v_lshlrev_b32_e32 v2, 16, v14
	v_mul_f32_e32 v3, v3, v3
	v_and_b32_e32 v4, 0xffff0000, v15
	v_fmac_f32_e32 v3, v2, v2
	v_lshlrev_b32_e32 v2, 16, v15
	v_mul_f32_e32 v4, v4, v4
	v_fmac_f32_e32 v4, v2, v2
	v_add_f32_e32 v2, v3, v4
	v_and_b32_e32 v4, 0xffff0000, v16
	v_lshlrev_b32_e32 v3, 16, v16
	v_mul_f32_e32 v4, v4, v4
	v_fmac_f32_e32 v4, v3, v3
	v_add_f32_e32 v2, v4, v2
	v_and_b32_e32 v4, 0xffff0000, v17
	v_lshlrev_b32_e32 v3, 16, v17
	v_mul_f32_e32 v4, v4, v4
	v_fmac_f32_e32 v4, v3, v3
	v_add_f32_e32 v8, v4, v2
	v_mov_b32_e32 v2, v130
	v_mov_b32_e32 v3, v131
	v_mov_b32_e32 v4, v132
	v_mov_b32_e32 v5, v133
	v_mov_b32_e32 v14, v138
	v_mov_b32_e32 v15, v139
	v_mov_b32_e32 v16, v140
	v_mov_b32_e32 v17, v141
	s_waitcnt lgkmcnt(0)
	v_lshlrev_b32_e32 v6, 16, v2
	v_and_b32_e32 v2, 0xffff0000, v2
	v_mul_f32_e32 v2, v2, v2
	v_fmac_f32_e32 v2, v6, v6
	v_lshlrev_b32_e32 v6, 16, v3
	v_and_b32_e32 v3, 0xffff0000, v3
	v_mul_f32_e32 v3, v3, v3
	v_fmac_f32_e32 v3, v6, v6
	v_add_f32_e32 v2, v2, v3
	v_lshlrev_b32_e32 v3, 16, v4
	v_and_b32_e32 v4, 0xffff0000, v4
	v_mul_f32_e32 v4, v4, v4
	v_fmac_f32_e32 v4, v3, v3
	v_add_f32_e32 v2, v4, v2
	v_and_b32_e32 v4, 0xffff0000, v5
	v_lshlrev_b32_e32 v3, 16, v5
	v_mul_f32_e32 v4, v4, v4
	v_fmac_f32_e32 v4, v3, v3
	v_add_f32_e32 v2, v4, v2
	v_and_b32_e32 v4, 0xffff0000, v14
	v_lshlrev_b32_e32 v3, 16, v14
	v_mul_f32_e32 v4, v4, v4
	v_and_b32_e32 v5, 0xffff0000, v15
	v_fmac_f32_e32 v4, v3, v3
	v_lshlrev_b32_e32 v3, 16, v15
	v_mul_f32_e32 v5, v5, v5
	v_fmac_f32_e32 v5, v3, v3
	v_add_f32_e32 v3, v4, v5
	v_and_b32_e32 v5, 0xffff0000, v16
	v_lshlrev_b32_e32 v4, 16, v16
	v_mul_f32_e32 v5, v5, v5
	v_fmac_f32_e32 v5, v4, v4
	v_add_f32_e32 v3, v5, v3
	v_and_b32_e32 v5, 0xffff0000, v17
	v_add_f32_e32 v2, v9, v2
	v_lshlrev_b32_e32 v4, 16, v17
	v_mul_f32_e32 v5, v5, v5
	v_fmac_f32_e32 v5, v4, v4
	ds_bpermute_b32 v4, v235, v2
	v_add_f32_e32 v3, v5, v3
	v_add_f32_e32 v3, v8, v3
	s_waitcnt lgkmcnt(0)
	v_add_f32_e32 v2, v2, v4
	ds_bpermute_b32 v4, v236, v2
	s_waitcnt lgkmcnt(0)
	v_add_f32_e32 v14, v2, v4
	ds_bpermute_b32 v2, v235, v3
	v_mad_i64_i32 v[4:5], s[0:1], s22, v230, v[86:87]
	ds_bpermute_b32 v15, v237, v14
	s_waitcnt lgkmcnt(1)
	v_add_f32_e32 v2, v3, v2
	ds_bpermute_b32 v3, v236, v2
	s_waitcnt lgkmcnt(0)
	v_add_f32_e32 v16, v2, v3
	v_add_co_u32_e32 v2, vcc, s3, v4
	ds_bpermute_b32 v17, v237, v16
	s_nop 0
	v_addc_co_u32_e32 v3, vcc, 0, v5, vcc
	v_mov_b32_e32 v6, v186
	v_mov_b32_e32 v7, v187
	v_mov_b32_e32 v8, v188
	v_mov_b32_e32 v9, v189
	v_add_co_u32_e32 v4, vcc, s89, v4
	s_nop 1
	v_addc_co_u32_e32 v5, vcc, 0, v5, vcc
	v_mov_b32_e32 v18, v194
	v_mov_b32_e32 v19, v195
	v_mov_b32_e32 v20, v196
	v_mov_b32_e32 v21, v197
	s_waitcnt lgkmcnt(0)
	v_lshlrev_b32_e32 v22, 16, v6
	v_and_b32_e32 v6, 0xffff0000, v6
	v_mul_f32_e32 v6, v6, v6
	v_fmac_f32_e32 v6, v22, v22
	v_lshlrev_b32_e32 v22, 16, v7
	v_and_b32_e32 v7, 0xffff0000, v7
	v_mul_f32_e32 v7, v7, v7
	v_fmac_f32_e32 v7, v22, v22
	v_add_f32_e32 v6, v6, v7
	v_lshlrev_b32_e32 v7, 16, v8
	v_and_b32_e32 v8, 0xffff0000, v8
	v_mul_f32_e32 v8, v8, v8
	v_fmac_f32_e32 v8, v7, v7
	v_add_f32_e32 v6, v8, v6
	v_and_b32_e32 v8, 0xffff0000, v9
	v_lshlrev_b32_e32 v7, 16, v9
	v_mul_f32_e32 v8, v8, v8
	v_fmac_f32_e32 v8, v7, v7
	v_and_b32_e32 v7, 0xffff0000, v18
	v_add_f32_e32 v22, v8, v6
	v_lshlrev_b32_e32 v6, 16, v18
	v_mul_f32_e32 v7, v7, v7
	v_and_b32_e32 v8, 0xffff0000, v19
	v_fmac_f32_e32 v7, v6, v6
	v_lshlrev_b32_e32 v6, 16, v19
	v_mul_f32_e32 v8, v8, v8
	v_fmac_f32_e32 v8, v6, v6
	v_add_f32_e32 v6, v7, v8
	v_and_b32_e32 v8, 0xffff0000, v20
	v_lshlrev_b32_e32 v7, 16, v20
	v_mul_f32_e32 v8, v8, v8
	v_fmac_f32_e32 v8, v7, v7
	v_add_f32_e32 v6, v8, v6
	v_and_b32_e32 v8, 0xffff0000, v21
	v_lshlrev_b32_e32 v7, 16, v21
	v_mul_f32_e32 v8, v8, v8
	v_fmac_f32_e32 v8, v7, v7
	v_add_f32_e32 v18, v8, v6
	v_mov_b32_e32 v6, v190
	v_mov_b32_e32 v7, v191
	v_mov_b32_e32 v8, v192
	v_mov_b32_e32 v9, v193
	s_nop 0
	v_mov_b32_e32 v2, v198
	v_mov_b32_e32 v3, v199
	v_mov_b32_e32 v4, v200
	v_mov_b32_e32 v5, v201
	s_waitcnt lgkmcnt(0)
; __device__ __forceinline__ void preproc_phase(Frame& F, int layer, int b, int cu_lo, int ncu) {
;     ...
;         {   float mq2 = 0.f, mk2 = 0.f;
; #pragma unroll
;             for (int a = 0; a < 4; ++a) { const bf16_t* rp = proj + (size_t)(t0 + a) * NP + c0; float sq = 0.f, sk = 0.f;
; #pragma unroll
;                 for (int hf = 0; hf < 2; ++hf) { const u32x4 qv = *(const u32x4*)(rp + C_FQ + 8 * hf), kv = *(const u32x4*)(rp + C_FK + 8 * hf);
;                     sq += (bflo(qv.x) * bflo(qv.x) + bfhi(qv.x) * bfhi(qv.x)) + (bflo(qv.y) * bflo(qv.y) + bfhi(qv.y) * bfhi(qv.y)) + (bflo(qv.z) * bflo(qv.z) + bfhi(qv.z) * bfhi(qv.z)) + (bflo(qv.w) * bflo(qv.w) + bfhi(qv.w) * bfhi(qv.w));
;                     sk += (bflo(kv.x) * bflo(kv.x) + bfhi(kv.x) * bfhi(kv.x)) + (bflo(kv.y) * bflo(kv.y) + bfhi(kv.y) * bfhi(kv.y)) + (bflo(kv.z) * bflo(kv.z) + bfhi(kv.z) * bfhi(kv.z)) + (bflo(kv.w) * bflo(kv.w) + bfhi(kv.w) * bfhi(kv.w)); }
;                 sq += __shfl_xor(sq, 1); sq += __shfl_xor(sq, 2); sq += __shfl_xor(sq, 4); sk += __shfl_xor(sk, 1); sk += __shfl_xor(sk, 2); sk += __shfl_xor(sk, 4);
;                 mq2 = fmaxf(mq2, sq); mk2 = fmaxf(mk2, sk); }
;             if ((F.lane & 7) == 0) { atomicMax(nrm, __builtin_bit_cast(unsigned, mq2 * 1.001f)); atomicMax(nrm + 8, __builtin_bit_cast(unsigned, mk2 * 1.001f)); } }
	v_lshlrev_b32_e32 v19, 16, v6
	v_and_b32_e32 v6, 0xffff0000, v6
	v_mul_f32_e32 v6, v6, v6
	v_fmac_f32_e32 v6, v19, v19
	v_lshlrev_b32_e32 v19, 16, v7
	v_and_b32_e32 v7, 0xffff0000, v7
	v_mul_f32_e32 v7, v7, v7
	v_fmac_f32_e32 v7, v19, v19
	v_add_f32_e32 v6, v6, v7
	v_lshlrev_b32_e32 v7, 16, v8
	v_and_b32_e32 v8, 0xffff0000, v8
	v_mul_f32_e32 v8, v8, v8
	v_fmac_f32_e32 v8, v7, v7
	v_add_f32_e32 v6, v8, v6
	v_and_b32_e32 v8, 0xffff0000, v9
	v_lshlrev_b32_e32 v7, 16, v9
	v_mul_f32_e32 v8, v8, v8
	v_fmac_f32_e32 v8, v7, v7
	v_lshlrev_b32_e32 v7, 16, v2
	v_and_b32_e32 v2, 0xffff0000, v2
	v_mul_f32_e32 v2, v2, v2
	v_fmac_f32_e32 v2, v7, v7
	v_lshlrev_b32_e32 v7, 16, v3
	v_and_b32_e32 v3, 0xffff0000, v3
	v_mul_f32_e32 v3, v3, v3
	v_fmac_f32_e32 v3, v7, v7
	v_add_f32_e32 v2, v2, v3
	v_lshlrev_b32_e32 v3, 16, v4
	v_and_b32_e32 v4, 0xffff0000, v4
	v_mul_f32_e32 v4, v4, v4
	v_fmac_f32_e32 v4, v3, v3
	v_add_f32_e32 v6, v8, v6
	v_add_f32_e32 v2, v4, v2
	v_and_b32_e32 v4, 0xffff0000, v5
	v_add_f32_e32 v6, v22, v6
	v_lshlrev_b32_e32 v3, 16, v5
	v_mul_f32_e32 v4, v4, v4
	v_fmac_f32_e32 v4, v3, v3
	ds_bpermute_b32 v3, v235, v6
	v_add_f32_e32 v2, v4, v2
	v_add_f32_e32 v2, v18, v2
	s_waitcnt lgkmcnt(0)
	v_add_f32_e32 v3, v6, v3
	ds_bpermute_b32 v4, v236, v3
	s_waitcnt lgkmcnt(0)
	v_add_f32_e32 v18, v3, v4
	ds_bpermute_b32 v3, v235, v2
	v_mad_i64_i32 v[4:5], s[0:1], s20, v230, v[86:87]
	ds_bpermute_b32 v19, v237, v18
	s_waitcnt lgkmcnt(1)
	v_add_f32_e32 v2, v2, v3
	ds_bpermute_b32 v3, v236, v2
	s_waitcnt lgkmcnt(0)
	v_add_f32_e32 v20, v2, v3
	v_add_co_u32_e32 v2, vcc, s3, v4
	ds_bpermute_b32 v21, v237, v20
	s_nop 0
	v_addc_co_u32_e32 v3, vcc, 0, v5, vcc
	v_mov_b32_e32 v22, v202
	v_mov_b32_e32 v23, v203
	v_mov_b32_e32 v24, v204
	v_mov_b32_e32 v25, v205
	v_add_co_u32_e32 v6, vcc, s89, v4
	s_nop 1
	v_addc_co_u32_e32 v7, vcc, 0, v5, vcc
	v_mov_b32_e32 v26, v210
	v_mov_b32_e32 v27, v211
	v_mov_b32_e32 v28, v212
	v_mov_b32_e32 v29, v213
	s_waitcnt lgkmcnt(0)
	v_and_b32_e32 v5, 0xffff0000, v22
	v_lshlrev_b32_e32 v4, 16, v22
	v_mul_f32_e32 v5, v5, v5
	v_and_b32_e32 v8, 0xffff0000, v23
	v_fmac_f32_e32 v5, v4, v4
	v_lshlrev_b32_e32 v4, 16, v23
	v_mul_f32_e32 v8, v8, v8
	v_fmac_f32_e32 v8, v4, v4
	v_add_f32_e32 v4, v5, v8
	v_and_b32_e32 v8, 0xffff0000, v24
	v_lshlrev_b32_e32 v5, 16, v24
	v_mul_f32_e32 v8, v8, v8
	v_fmac_f32_e32 v8, v5, v5
	v_add_f32_e32 v4, v8, v4
	v_and_b32_e32 v8, 0xffff0000, v25
	v_lshlrev_b32_e32 v5, 16, v25
	v_mul_f32_e32 v8, v8, v8
	v_fmac_f32_e32 v8, v5, v5
	v_and_b32_e32 v5, 0xffff0000, v26
	v_add_f32_e32 v23, v8, v4
	v_lshlrev_b32_e32 v4, 16, v26
	v_mul_f32_e32 v5, v5, v5
	v_and_b32_e32 v8, 0xffff0000, v27
	v_fmac_f32_e32 v5, v4, v4
	v_lshlrev_b32_e32 v4, 16, v27
	v_mul_f32_e32 v8, v8, v8
	v_fmac_f32_e32 v8, v4, v4
	v_add_f32_e32 v4, v5, v8
	v_and_b32_e32 v8, 0xffff0000, v28
	v_lshlrev_b32_e32 v5, 16, v28
	v_mul_f32_e32 v8, v8, v8
	v_fmac_f32_e32 v8, v5, v5
	v_add_f32_e32 v4, v8, v4
	v_and_b32_e32 v8, 0xffff0000, v29
	v_lshlrev_b32_e32 v5, 16, v29
	v_mul_f32_e32 v8, v8, v8
	v_fmac_f32_e32 v8, v5, v5
	v_add_f32_e32 v22, v8, v4
	v_mov_b32_e32 v2, v206
	v_mov_b32_e32 v3, v207
	v_mov_b32_e32 v4, v208
	v_mov_b32_e32 v5, v209
	s_nop 0
	v_mov_b32_e32 v6, v214
	v_mov_b32_e32 v7, v215
	v_mov_b32_e32 v8, v216
	v_mov_b32_e32 v9, v217
	s_waitcnt lgkmcnt(0)
	v_lshlrev_b32_e32 v24, 16, v2
	v_and_b32_e32 v2, 0xffff0000, v2
	v_mul_f32_e32 v2, v2, v2
	v_fmac_f32_e32 v2, v24, v24
	v_lshlrev_b32_e32 v24, 16, v3
	v_and_b32_e32 v3, 0xffff0000, v3
	v_mul_f32_e32 v3, v3, v3
	v_fmac_f32_e32 v3, v24, v24
	v_add_f32_e32 v2, v2, v3
	v_lshlrev_b32_e32 v3, 16, v4
	v_and_b32_e32 v4, 0xffff0000, v4
	v_mul_f32_e32 v4, v4, v4
	v_fmac_f32_e32 v4, v3, v3
	v_add_f32_e32 v2, v4, v2
	v_and_b32_e32 v4, 0xffff0000, v5
	v_lshlrev_b32_e32 v3, 16, v5
	v_mul_f32_e32 v4, v4, v4
	v_fmac_f32_e32 v4, v3, v3
	v_add_f32_e32 v2, v4, v2
	v_and_b32_e32 v4, 0xffff0000, v6
	v_lshlrev_b32_e32 v3, 16, v6
	v_mul_f32_e32 v4, v4, v4
	v_and_b32_e32 v5, 0xffff0000, v7
	v_fmac_f32_e32 v4, v3, v3
	v_lshlrev_b32_e32 v3, 16, v7
	v_mul_f32_e32 v5, v5, v5
	v_fmac_f32_e32 v5, v3, v3
	v_add_f32_e32 v3, v4, v5
	v_and_b32_e32 v5, 0xffff0000, v8
	v_lshlrev_b32_e32 v4, 16, v8
	v_mul_f32_e32 v5, v5, v5
	v_fmac_f32_e32 v5, v4, v4
	v_add_f32_e32 v3, v5, v3
	v_and_b32_e32 v5, 0xffff0000, v9
	v_lshlrev_b32_e32 v4, 16, v9
	v_mul_f32_e32 v5, v5, v5
	v_fmac_f32_e32 v5, v4, v4
	v_add_f32_e32 v3, v5, v3
	v_add_f32_e32 v2, v23, v2
	v_add_f32_e32 v4, v22, v3
	ds_bpermute_b32 v3, v235, v2
	ds_bpermute_b32 v5, v235, v4
	s_waitcnt lgkmcnt(1)
	v_add_f32_e32 v2, v2, v3
	s_waitcnt lgkmcnt(0)
	v_add_f32_e32 v4, v4, v5
	ds_bpermute_b32 v3, v236, v2
	ds_bpermute_b32 v5, v236, v4
	s_waitcnt lgkmcnt(1)
	v_add_f32_e32 v2, v2, v3
	s_waitcnt lgkmcnt(0)
	v_add_f32_e32 v4, v4, v5
	ds_bpermute_b32 v3, v237, v2
	ds_bpermute_b32 v5, v237, v4
	s_and_saveexec_b64 s[0:1], s[6:7]
	s_cbranch_execz .LBB0_325
	v_add_f32_e32 v6, v12, v13
	v_add_f32_e32 v7, v16, v17
	v_max3_f32 v6, v6, 0, v7
	v_add_f32_e32 v7, v20, v21
	s_waitcnt lgkmcnt(0)
	v_add_f32_e32 v4, v4, v5
	v_max3_f32 v4, v6, v7, v4
	v_add_f32_e32 v5, v10, v11
	v_add_f32_e32 v6, v14, v15
	v_max3_f32 v5, v5, 0, v6
	v_add_f32_e32 v6, v18, v19
	v_add_f32_e32 v2, v2, v3
	v_max3_f32 v2, v5, v6, v2
	v_mul_f32_e32 v2, 0x3f8020c5, v2
	v_mul_f32_e32 v3, 0x3f8020c5, v4
	flat_atomic_umax v[84:85], v2
	flat_atomic_umax v[84:85], v3 offset:32
